# fp6 loops: s_setprio 1 in load segments, 0 in MFMA segments (loading wave gets issue priority)
# baseline (speedup 1.0000x reference)
.LBB0_991:
	ds_read_b128 v[146:149], v142
	ds_read_b128 v[192:195], v142 offset:1024
	ds_read_b128 v[152:155], v142 offset:2048
	ds_read_b128 v[196:199], v142 offset:3072
	ds_read_b128 v[158:161], v143
	ds_read_b128 v[200:203], v143 offset:1024
	ds_read_b128 v[164:167], v143 offset:2048
	ds_read_b128 v[204:207], v143 offset:3072
	v_lshl_add_u64 v[150:151], s[54:55], 0, v[136:137]
	s_add_i32 m0, s29, 0xc000
	ds_read_b128 v[170:173], v144
	ds_read_b128 v[208:211], v144 offset:1024
	ds_read_b128 v[176:179], v144 offset:2048
	ds_read_b128 v[212:215], v144 offset:3072
	ds_read_b128 v[182:185], v144 offset:4096
	ds_read_b128 v[216:219], v144 offset:5120
	ds_read_b128 v[188:191], v144 offset:6144
	ds_read_b128 v[220:223], v144 offset:7168
	global_load_lds_dwordx4 v[150:151], off
	s_add_i32 m0, s29, 0xe000
	v_lshl_add_u64 v[150:151], v[150:151], 0, s[10:11]
	global_load_lds_dwordx4 v[150:151], off
	s_waitcnt vmcnt(8)
	s_waitcnt lgkmcnt(0)
	s_barrier
	s_setprio 0
	s_waitcnt lgkmcnt(0)
	v_mov_b32_e32 v150, v192
	v_mov_b32_e32 v151, v193
	v_mov_b32_e32 v156, v196
	v_mov_b32_e32 v157, v197
	v_mov_b32_e32 v174, v208
	v_mov_b32_e32 v175, v209
	v_mov_b32_e32 v180, v212
	v_mov_b32_e32 v181, v213
	v_mov_b32_e32 v186, v216
	v_mov_b32_e32 v187, v217
	v_mov_b32_e32 v192, v220
	v_mov_b32_e32 v193, v221
	v_mfma_scale_f32_16x16x128_f8f6f4 v[128:131], v[146:151], v[170:175], v[128:131], v194, v210 op_sel_hi:[0,0,0] cbsz:2 blgp:2
	v_mfma_scale_f32_16x16x128_f8f6f4 v[124:127], v[152:157], v[170:175], v[124:127], v198, v210 op_sel_hi:[0,0,0] cbsz:2 blgp:2
	v_mfma_scale_f32_16x16x128_f8f6f4 v[120:123], v[146:151], v[176:181], v[120:123], v194, v214 op_sel_hi:[0,0,0] cbsz:2 blgp:2
	v_mfma_scale_f32_16x16x128_f8f6f4 v[116:119], v[152:157], v[176:181], v[116:119], v198, v214 op_sel_hi:[0,0,0] cbsz:2 blgp:2
	s_add_u32 s56, s54, 0xfffc0080
	s_addc_u32 s57, s55, -1
	s_cmp_eq_u32 s86, 12
	s_cselect_b32 s57, s4, s57
	s_cselect_b32 s56, s5, s56
	s_cselect_b32 s59, s39, s85
	s_cselect_b32 s58, s45, s84
	s_add_i32 s100, s61, s24
	s_add_i32 s101, s62, s24
	v_lshl_add_u64 v[236:237], s[58:59], 0, v[132:133]
	v_lshl_add_u64 v[238:239], s[56:57], 0, v[134:135]
	v_lshl_add_u64 v[240:241], v[236:237], 0, s[10:11]
	v_lshl_add_u64 v[242:243], v[236:237], 0, s[12:13]
	v_lshl_add_u64 v[244:245], v[236:237], 0, s[14:15]
	v_lshl_add_u64 v[246:247], v[238:239], 0, s[10:11]
	v_mfma_scale_f32_16x16x128_f8f6f4 v[112:115], v[146:151], v[182:187], v[112:115], v194, v218 op_sel_hi:[0,0,0] cbsz:2 blgp:2
	v_mfma_scale_f32_16x16x128_f8f6f4 v[108:111], v[152:157], v[182:187], v[108:111], v198, v218 op_sel_hi:[0,0,0] cbsz:2 blgp:2
	v_mfma_scale_f32_16x16x128_f8f6f4 v[104:107], v[146:151], v[188:193], v[104:107], v194, v222 op_sel_hi:[0,0,0] cbsz:2 blgp:2
	v_mfma_scale_f32_16x16x128_f8f6f4 v[100:103], v[152:157], v[188:193], v[100:103], v198, v222 op_sel_hi:[0,0,0] cbsz:2 blgp:2
	v_mov_b32_e32 v168, v204
	v_mov_b32_e32 v169, v205
	v_mov_b32_e32 v162, v200
	v_mov_b32_e32 v163, v201
	v_mfma_scale_f32_16x16x128_f8f6f4 v[30:33], v[164:169], v[188:193], v[30:33], v206, v222 op_sel_hi:[0,0,0] cbsz:2 blgp:2
	s_nop 0
	v_mfma_scale_f32_16x16x128_f8f6f4 v[224:227], v[158:163], v[170:175], v[2:5], v202, v210 op_sel_hi:[0,0,0] cbsz:2 blgp:2
	v_mfma_scale_f32_16x16x128_f8f6f4 v[170:173], v[164:169], v[170:175], v[6:9], v206, v210 op_sel_hi:[0,0,0] cbsz:2 blgp:2
	v_mfma_scale_f32_16x16x128_f8f6f4 v[208:211], v[158:163], v[176:181], v[10:13], v202, v214 op_sel_hi:[0,0,0] cbsz:2 blgp:2
	v_mfma_scale_f32_16x16x128_f8f6f4 v[174:177], v[164:169], v[176:181], v[14:17], v206, v214 op_sel_hi:[0,0,0] cbsz:2 blgp:2
	v_mfma_scale_f32_16x16x128_f8f6f4 v[178:181], v[158:163], v[182:187], v[18:21], v202, v218 op_sel_hi:[0,0,0] cbsz:2 blgp:2
	v_mfma_scale_f32_16x16x128_f8f6f4 v[182:185], v[164:169], v[182:187], v[22:25], v206, v218 op_sel_hi:[0,0,0] cbsz:2 blgp:2
	v_mfma_scale_f32_16x16x128_f8f6f4 v[212:215], v[158:163], v[188:193], v[26:29], v202, v222 op_sel_hi:[0,0,0] cbsz:2 blgp:2
	s_barrier
	s_setprio 1
	s_mov_b32 m0, s100
	ds_read_b128 v[2:5], v144 offset:16384
	ds_read_b128 v[24:27], v144 offset:17408
	ds_read_b128 v[8:11], v144 offset:18432
	global_load_lds_dwordx4 v[236:237], off
	s_add_i32 m0, s100, 0x2000
	ds_read_b128 v[186:189], v144 offset:19456
	global_load_lds_dwordx4 v[240:241], off
	s_mov_b32 m0, s101
	ds_read_b128 v[14:17], v144 offset:20480
	global_load_lds_dwordx4 v[242:243], off
	s_add_i32 m0, s101, 0x2000
	ds_read_b128 v[190:193], v144 offset:21504
	global_load_lds_dwordx4 v[244:245], off
	s_mov_b32 m0, s29
	ds_read_b128 v[20:23], v144 offset:22528
	global_load_lds_dwordx4 v[238:239], off
	s_mov_b32 m0, s33
	ds_read_b128 v[216:219], v144 offset:23552
	global_load_lds_dwordx4 v[246:247], off
	s_waitcnt vmcnt(8)
	s_waitcnt lgkmcnt(0)
	s_barrier
	s_setprio 0
	s_waitcnt lgkmcnt(0)
	v_mov_b32_e32 v6, v24
	v_mov_b32_e32 v7, v25
	v_mov_b32_e32 v12, v186
	v_mov_b32_e32 v13, v187
	v_mov_b32_e32 v18, v190
	v_mov_b32_e32 v19, v191
	v_mfma_scale_f32_16x16x128_f8f6f4 v[96:99], v[146:151], v[2:7], v[96:99], v194, v26 op_sel_hi:[0,0,0] cbsz:2 blgp:2
	v_mov_b32_e32 v24, v216
	v_mov_b32_e32 v25, v217
	v_mfma_scale_f32_16x16x128_f8f6f4 v[92:95], v[152:157], v[2:7], v[92:95], v198, v26 op_sel_hi:[0,0,0] cbsz:2 blgp:2
	v_mfma_scale_f32_16x16x128_f8f6f4 v[80:83], v[146:151], v[8:13], v[80:83], v194, v188 op_sel_hi:[0,0,0] cbsz:2 blgp:2
	v_mfma_scale_f32_16x16x128_f8f6f4 v[76:79], v[152:157], v[8:13], v[76:79], v198, v188 op_sel_hi:[0,0,0] cbsz:2 blgp:2
	s_add_i32 s56, 0, 0x18000
	s_add_i32 s57, 0, 0x1c000
	v_add_u32_e32 v252, 0x18000, v1
	v_add_u32_e32 v253, 0x1c000, v1
	v_lshl_add_u64 v[248:249], v[238:239], 0, s[12:13]
	v_lshl_add_u64 v[250:251], v[238:239], 0, s[14:15]
	v_mfma_scale_f32_16x16x128_f8f6f4 v[68:71], v[146:151], v[14:19], v[68:71], v194, v192 op_sel_hi:[0,0,0] cbsz:2 blgp:2
	v_mfma_scale_f32_16x16x128_f8f6f4 v[56:59], v[152:157], v[14:19], v[56:59], v198, v192 op_sel_hi:[0,0,0] cbsz:2 blgp:2
	v_mfma_scale_f32_16x16x128_f8f6f4 v[194:197], v[146:151], v[20:25], v[52:55], v194, v218 op_sel_hi:[0,0,0] cbsz:2 blgp:2
	v_mfma_scale_f32_16x16x128_f8f6f4 v[198:201], v[152:157], v[20:25], v[44:47], v198, v218 op_sel_hi:[0,0,0] cbsz:2 blgp:2
	v_mfma_scale_f32_16x16x128_f8f6f4 v[88:91], v[158:163], v[2:7], v[88:91], v202, v26 op_sel_hi:[0,0,0] cbsz:2 blgp:2
	v_mfma_scale_f32_16x16x128_f8f6f4 v[84:87], v[164:169], v[2:7], v[84:87], v206, v26 op_sel_hi:[0,0,0] cbsz:2 blgp:2
	v_mfma_scale_f32_16x16x128_f8f6f4 v[72:75], v[158:163], v[8:13], v[72:75], v202, v188 op_sel_hi:[0,0,0] cbsz:2 blgp:2
	v_mfma_scale_f32_16x16x128_f8f6f4 v[186:189], v[164:169], v[8:13], v[64:67], v206, v188 op_sel_hi:[0,0,0] cbsz:2 blgp:2
	v_mfma_scale_f32_16x16x128_f8f6f4 v[220:223], v[158:163], v[14:19], v[60:63], v202, v192 op_sel_hi:[0,0,0] cbsz:2 blgp:2
	v_mfma_scale_f32_16x16x128_f8f6f4 v[190:193], v[164:169], v[14:19], v[48:51], v206, v192 op_sel_hi:[0,0,0] cbsz:2 blgp:2
	v_mfma_scale_f32_16x16x128_f8f6f4 v[202:205], v[158:163], v[20:25], v[40:43], v202, v218 op_sel_hi:[0,0,0] cbsz:2 blgp:2
	v_mfma_scale_f32_16x16x128_f8f6f4 v[216:219], v[164:169], v[20:25], v[36:39], v206, v218 op_sel_hi:[0,0,0] cbsz:2 blgp:2
	s_barrier
	s_setprio 1
	s_mov_b32 m0, s40
	ds_read_b128 v[36:39], v252
	ds_read_b128 v[52:55], v252 offset:1024
	ds_read_b128 v[42:45], v252 offset:2048
	ds_read_b128 v[64:67], v252 offset:3072
	ds_read_b128 v[146:149], v253
	ds_read_b128 v[228:231], v253 offset:1024
	ds_read_b128 v[152:155], v253 offset:2048
	ds_read_b128 v[232:235], v253 offset:3072
	ds_read_b128 v[6:9], v144 offset:32768
	ds_read_b128 v[10:13], v144 offset:33792
	ds_read_b128 v[14:17], v144 offset:34816
	ds_read_b128 v[18:21], v144 offset:35840
	ds_read_b128 v[22:25], v144 offset:36864
	ds_read_b128 v[26:29], v144 offset:37888
	global_load_lds_dwordx4 v[248:249], off
	s_mov_b32 m0, s41
	ds_read_b128 v[48:51], v144 offset:38912
	ds_read_b128 v[60:63], v144 offset:39936
	global_load_lds_dwordx4 v[250:251], off
	s_waitcnt vmcnt(8)
	s_waitcnt lgkmcnt(0)
	s_barrier
	s_setprio 0
	s_waitcnt lgkmcnt(0)
	v_mov_b32_e32 v40, v52
	v_mov_b32_e32 v41, v53
	v_mov_b32_e32 v46, v64
	v_mov_b32_e32 v47, v65
	v_mov_b32_e32 v52, v60
	v_mov_b32_e32 v53, v61
	v_mfma_scale_f32_16x16x128_f8f6f4 v[128:131], v[36:41], v[6:11], v[128:131], v54, v12 op_sel_hi:[0,0,0] cbsz:2 blgp:2
	v_mfma_scale_f32_16x16x128_f8f6f4 v[124:127], v[42:47], v[6:11], v[124:127], v66, v12 op_sel_hi:[0,0,0] cbsz:2 blgp:2
	v_mfma_scale_f32_16x16x128_f8f6f4 v[120:123], v[36:41], v[14:19], v[120:123], v54, v20 op_sel_hi:[0,0,0] cbsz:2 blgp:2
	v_mfma_scale_f32_16x16x128_f8f6f4 v[116:119], v[42:47], v[14:19], v[116:119], v66, v20 op_sel_hi:[0,0,0] cbsz:2 blgp:2
	s_add_i32 s100, s56, s24
	s_add_i32 s101, s57, s24
	s_add_i32 s56, s57, s24
	v_lshl_add_u64 v[240:241], v[236:237], 0, s[22:23]
	v_lshl_add_u64 v[242:243], v[236:237], 0, s[26:27]
	v_lshl_add_u64 v[244:245], v[236:237], 0, s[30:31]
	v_lshl_add_u64 v[246:247], v[236:237], 0, s[34:35]
	v_lshl_add_u64 v[248:249], v[238:239], 0, s[22:23]
	v_lshl_add_u64 v[250:251], v[238:239], 0, s[26:27]
	v_mfma_scale_f32_16x16x128_f8f6f4 v[112:115], v[36:41], v[22:27], v[112:115], v54, v28 op_sel_hi:[0,0,0] cbsz:2 blgp:2
	v_mfma_scale_f32_16x16x128_f8f6f4 v[108:111], v[42:47], v[22:27], v[108:111], v66, v28 op_sel_hi:[0,0,0] cbsz:2 blgp:2
	v_mfma_scale_f32_16x16x128_f8f6f4 v[104:107], v[36:41], v[48:53], v[104:107], v54, v62 op_sel_hi:[0,0,0] cbsz:2 blgp:2
	v_mfma_scale_f32_16x16x128_f8f6f4 v[100:103], v[42:47], v[48:53], v[100:103], v66, v62 op_sel_hi:[0,0,0] cbsz:2 blgp:2
	v_mov_b32_e32 v150, v228
	v_mov_b32_e32 v151, v229
	v_mov_b32_e32 v156, v232
	v_mov_b32_e32 v157, v233
	v_mfma_scale_f32_16x16x128_f8f6f4 v[2:5], v[146:151], v[6:11], v[224:227], v230, v12 op_sel_hi:[0,0,0] cbsz:2 blgp:2
	s_nop 0
	v_mfma_scale_f32_16x16x128_f8f6f4 v[6:9], v[152:157], v[6:11], v[170:173], v234, v12 op_sel_hi:[0,0,0] cbsz:2 blgp:2
	v_mfma_scale_f32_16x16x128_f8f6f4 v[10:13], v[146:151], v[14:19], v[208:211], v230, v20 op_sel_hi:[0,0,0] cbsz:2 blgp:2
	v_mfma_scale_f32_16x16x128_f8f6f4 v[14:17], v[152:157], v[14:19], v[174:177], v234, v20 op_sel_hi:[0,0,0] cbsz:2 blgp:2
	v_mfma_scale_f32_16x16x128_f8f6f4 v[18:21], v[146:151], v[22:27], v[178:181], v230, v28 op_sel_hi:[0,0,0] cbsz:2 blgp:2
	v_mfma_scale_f32_16x16x128_f8f6f4 v[22:25], v[152:157], v[22:27], v[182:185], v234, v28 op_sel_hi:[0,0,0] cbsz:2 blgp:2
	v_mfma_scale_f32_16x16x128_f8f6f4 v[26:29], v[146:151], v[48:53], v[212:215], v230, v62 op_sel_hi:[0,0,0] cbsz:2 blgp:2
	v_mfma_scale_f32_16x16x128_f8f6f4 v[30:33], v[152:157], v[48:53], v[30:33], v234, v62 op_sel_hi:[0,0,0] cbsz:2 blgp:2
	s_barrier
	s_setprio 1
	s_mov_b32 m0, s100
	ds_read_b128 v[60:63], v144 offset:49152
	ds_read_b128 v[48:51], v144 offset:50176
	ds_read_b128 v[158:161], v144 offset:51200
	global_load_lds_dwordx4 v[240:241], off
	s_add_i32 m0, s100, 0x2000
	ds_read_b128 v[174:177], v144 offset:52224
	global_load_lds_dwordx4 v[242:243], off
	s_mov_b32 m0, s101
	ds_read_b128 v[164:167], v144 offset:53248
	global_load_lds_dwordx4 v[244:245], off
	s_add_i32 m0, s101, 0x2000
	ds_read_b128 v[178:181], v144 offset:54272
	global_load_lds_dwordx4 v[246:247], off
	s_mov_b32 m0, s43
	ds_read_b128 v[170:173], v144 offset:55296
	global_load_lds_dwordx4 v[248:249], off
	s_mov_b32 m0, s50
	ds_read_b128 v[182:185], v144 offset:56320
	global_load_lds_dwordx4 v[250:251], off
	s_waitcnt vmcnt(8)
	s_waitcnt lgkmcnt(0)
	s_barrier
	s_setprio 0
	s_waitcnt lgkmcnt(0)
	v_mov_b32_e32 v64, v48
	v_mov_b32_e32 v65, v49
	v_mov_b32_e32 v162, v174
	v_mov_b32_e32 v163, v175
	v_mov_b32_e32 v168, v178
	v_mov_b32_e32 v169, v179
	v_mov_b32_e32 v174, v182
	v_mov_b32_e32 v175, v183
	v_mfma_scale_f32_16x16x128_f8f6f4 v[96:99], v[36:41], v[60:65], v[96:99], v54, v50 op_sel_hi:[0,0,0] cbsz:2 blgp:2
	v_mfma_scale_f32_16x16x128_f8f6f4 v[92:95], v[42:47], v[60:65], v[92:95], v66, v50 op_sel_hi:[0,0,0] cbsz:2 blgp:2
	v_mfma_scale_f32_16x16x128_f8f6f4 v[80:83], v[36:41], v[158:163], v[80:83], v54, v176 op_sel_hi:[0,0,0] cbsz:2 blgp:2
	v_mfma_scale_f32_16x16x128_f8f6f4 v[76:79], v[42:47], v[158:163], v[76:79], v66, v176 op_sel_hi:[0,0,0] cbsz:2 blgp:2
	s_add_i32 s86, s86, 2
	s_add_u32 s54, s54, 0x100
	s_addc_u32 s55, s55, 0
	s_add_u32 s84, s84, 0x100
	s_addc_u32 s85, s85, 0
	v_mfma_scale_f32_16x16x128_f8f6f4 v[68:71], v[36:41], v[164:169], v[68:71], v54, v180 op_sel_hi:[0,0,0] cbsz:2 blgp:2
	v_mfma_scale_f32_16x16x128_f8f6f4 v[56:59], v[42:47], v[164:169], v[56:59], v66, v180 op_sel_hi:[0,0,0] cbsz:2 blgp:2
	v_mfma_scale_f32_16x16x128_f8f6f4 v[52:55], v[36:41], v[170:175], v[194:197], v54, v184 op_sel_hi:[0,0,0] cbsz:2 blgp:2
	v_mfma_scale_f32_16x16x128_f8f6f4 v[44:47], v[42:47], v[170:175], v[198:201], v66, v184 op_sel_hi:[0,0,0] cbsz:2 blgp:2
	v_mfma_scale_f32_16x16x128_f8f6f4 v[88:91], v[146:151], v[60:65], v[88:91], v230, v50 op_sel_hi:[0,0,0] cbsz:2 blgp:2
	v_mfma_scale_f32_16x16x128_f8f6f4 v[84:87], v[152:157], v[60:65], v[84:87], v234, v50 op_sel_hi:[0,0,0] cbsz:2 blgp:2
	v_mfma_scale_f32_16x16x128_f8f6f4 v[72:75], v[146:151], v[158:163], v[72:75], v230, v176 op_sel_hi:[0,0,0] cbsz:2 blgp:2
	v_mfma_scale_f32_16x16x128_f8f6f4 v[64:67], v[152:157], v[158:163], v[186:189], v234, v176 op_sel_hi:[0,0,0] cbsz:2 blgp:2
	v_mfma_scale_f32_16x16x128_f8f6f4 v[60:63], v[146:151], v[164:169], v[220:223], v230, v180 op_sel_hi:[0,0,0] cbsz:2 blgp:2
	v_mfma_scale_f32_16x16x128_f8f6f4 v[48:51], v[152:157], v[164:169], v[190:193], v234, v180 op_sel_hi:[0,0,0] cbsz:2 blgp:2
	v_mfma_scale_f32_16x16x128_f8f6f4 v[40:43], v[146:151], v[170:175], v[202:205], v230, v184 op_sel_hi:[0,0,0] cbsz:2 blgp:2
	v_mfma_scale_f32_16x16x128_f8f6f4 v[36:39], v[152:157], v[170:175], v[216:219], v234, v184 op_sel_hi:[0,0,0] cbsz:2 blgp:2
	s_barrier
	s_setprio 1
	s_cmp_gt_u32 s86, 13
	s_cbranch_scc0 .LBB0_991
	s_setprio 0
	s_and_b64 vcc, exec, s[36:37]
	s_cbranch_vccz .LBB0_994
	s_barrier

.LBB0_1074:
	ds_read_b128 v[114:117], v176
	ds_read_b128 v[142:145], v176 offset:1024
	ds_read_b128 v[120:123], v176 offset:2048
	ds_read_b128 v[172:175], v176 offset:3072
	ds_read_b128 v[126:129], v177
	ds_read_b128 v[198:201], v177 offset:1024
	ds_read_b128 v[132:135], v177 offset:2048
	ds_read_b128 v[202:205], v177 offset:3072
	s_add_u32 s52, s48, 0xfff50080
	s_addc_u32 s53, s49, -1
	s_cmp_eq_u32 s63, 40
	s_cselect_b32 s53, s9, s53
	s_cselect_b32 s52, s8, s52
	s_cselect_b32 s55, s47, s5
	s_cselect_b32 s54, s46, s4
	v_lshl_add_u64 v[118:119], s[48:49], 0, v[166:167]
	s_add_i32 m0, s28, 0xc000
	ds_read_b128 v[138:141], v178
	ds_read_b128 v[206:209], v178 offset:1024
	ds_read_b128 v[180:183], v178 offset:2048
	ds_read_b128 v[210:213], v178 offset:3072
	ds_read_b128 v[186:189], v178 offset:4096
	ds_read_b128 v[214:217], v178 offset:5120
	ds_read_b128 v[192:195], v178 offset:6144
	ds_read_b128 v[218:221], v178 offset:7168
	global_load_lds_dwordx4 v[118:119], off
	v_lshl_add_u64 v[118:119], v[118:119], 0, s[12:13]
	s_add_i32 m0, s28, 0xe000
	s_nop 0
	global_load_lds_dwordx4 v[118:119], off
	s_waitcnt vmcnt(8)
	s_waitcnt lgkmcnt(0)
	s_barrier
	s_setprio 0
	s_waitcnt lgkmcnt(0)
	v_mov_b32_e32 v118, v142
	v_mov_b32_e32 v119, v143
	v_mov_b32_e32 v124, v172
	v_mov_b32_e32 v125, v173
	v_mov_b32_e32 v142, v206
	v_mov_b32_e32 v143, v207
	v_mov_b32_e32 v184, v210
	v_mov_b32_e32 v185, v211
	v_mov_b32_e32 v190, v214
	v_mov_b32_e32 v191, v215
	v_mfma_scale_f32_16x16x128_f8f6f4 v[158:161], v[114:119], v[138:143], v[158:161], v144, v208 op_sel_hi:[0,0,0] cbsz:2 blgp:2
	v_mov_b32_e32 v196, v218
	v_mov_b32_e32 v197, v219
	v_mfma_scale_f32_16x16x128_f8f6f4 v[154:157], v[120:125], v[138:143], v[154:157], v174, v208 op_sel_hi:[0,0,0] cbsz:2 blgp:2
	v_mfma_scale_f32_16x16x128_f8f6f4 v[110:113], v[114:119], v[180:185], v[110:113], v144, v212 op_sel_hi:[0,0,0] cbsz:2 blgp:2
	v_mfma_scale_f32_16x16x128_f8f6f4 v[106:109], v[120:125], v[180:185], v[106:109], v174, v212 op_sel_hi:[0,0,0] cbsz:2 blgp:2
	v_mfma_scale_f32_16x16x128_f8f6f4 v[94:97], v[114:119], v[186:191], v[94:97], v144, v216 op_sel_hi:[0,0,0] cbsz:2 blgp:2
	v_mfma_scale_f32_16x16x128_f8f6f4 v[90:93], v[120:125], v[186:191], v[90:93], v174, v216 op_sel_hi:[0,0,0] cbsz:2 blgp:2
	v_mfma_scale_f32_16x16x128_f8f6f4 v[222:225], v[114:119], v[192:197], v[78:81], v144, v220 op_sel_hi:[0,0,0] cbsz:2 blgp:2
	v_mfma_scale_f32_16x16x128_f8f6f4 v[226:229], v[120:125], v[192:197], v[74:77], v174, v220 op_sel_hi:[0,0,0] cbsz:2 blgp:2
	v_mov_b32_e32 v130, v198
	v_mov_b32_e32 v131, v199
	v_mov_b32_e32 v136, v202
	v_mov_b32_e32 v137, v203
	v_mfma_scale_f32_16x16x128_f8f6f4 v[150:153], v[126:131], v[138:143], v[150:153], v200, v208 op_sel_hi:[0,0,0] cbsz:2 blgp:2
	v_mfma_scale_f32_16x16x128_f8f6f4 v[102:105], v[126:131], v[180:185], v[102:105], v200, v212 op_sel_hi:[0,0,0] cbsz:2 blgp:2
	v_mfma_scale_f32_16x16x128_f8f6f4 v[98:101], v[132:137], v[180:185], v[98:101], v204, v212 op_sel_hi:[0,0,0] cbsz:2 blgp:2
	v_mfma_scale_f32_16x16x128_f8f6f4 v[138:141], v[132:137], v[138:143], v[146:149], v204, v208 op_sel_hi:[0,0,0] cbsz:2 blgp:2
	v_mfma_scale_f32_16x16x128_f8f6f4 v[180:183], v[126:131], v[186:191], v[86:89], v200, v216 op_sel_hi:[0,0,0] cbsz:2 blgp:2
	v_mfma_scale_f32_16x16x128_f8f6f4 v[184:187], v[132:137], v[186:191], v[82:85], v204, v216 op_sel_hi:[0,0,0] cbsz:2 blgp:2
	v_mfma_scale_f32_16x16x128_f8f6f4 v[188:191], v[126:131], v[192:197], v[70:73], v200, v220 op_sel_hi:[0,0,0] cbsz:2 blgp:2
	v_mfma_scale_f32_16x16x128_f8f6f4 v[192:195], v[132:137], v[192:197], v[66:69], v204, v220 op_sel_hi:[0,0,0] cbsz:2 blgp:2
	s_barrier
	s_setprio 1
	v_lshl_add_u64 v[250:251], s[54:55], 0, v[164:165]
	s_add_i32 s54, s64, s25
	s_mov_b32 m0, s54
	ds_read_b128 v[66:69], v178 offset:16384
	ds_read_b128 v[146:149], v178 offset:17408
	ds_read_b128 v[72:75], v178 offset:18432
	ds_read_b128 v[196:199], v178 offset:19456
	ds_read_b128 v[78:81], v178 offset:20480
	ds_read_b128 v[206:209], v178 offset:21504
	ds_read_b128 v[84:87], v178 offset:22528
	ds_read_b128 v[210:213], v178 offset:23552
	global_load_lds_dwordx4 v[250:251], off
	v_lshl_add_u64 v[70:71], v[250:251], 0, s[12:13]
	s_add_i32 m0, s54, 0x2000
	s_add_i32 s54, s65, s25
	global_load_lds_dwordx4 v[70:71], off
	v_lshl_add_u64 v[70:71], v[250:251], 0, s[14:15]
	s_mov_b32 m0, s54
	v_lshl_add_u64 v[252:253], s[52:53], 0, v[162:163]
	global_load_lds_dwordx4 v[70:71], off
	v_lshl_add_u64 v[70:71], v[250:251], 0, s[16:17]
	s_add_i32 m0, s54, 0x2000
	s_nop 0
	global_load_lds_dwordx4 v[70:71], off
	s_mov_b32 m0, s28
	v_lshl_add_u64 v[70:71], v[252:253], 0, s[12:13]
	global_load_lds_dwordx4 v[252:253], off
	s_mov_b32 m0, s29
	s_nop 0
	global_load_lds_dwordx4 v[70:71], off
	s_waitcnt vmcnt(8)
	s_waitcnt lgkmcnt(0)
	s_barrier
	s_setprio 0
	s_waitcnt lgkmcnt(0)
	v_mov_b32_e32 v70, v146
	v_mov_b32_e32 v71, v147
	v_mov_b32_e32 v76, v196
	v_mov_b32_e32 v77, v197
	v_mfma_scale_f32_16x16x128_f8f6f4 v[62:65], v[114:119], v[66:71], v[62:65], v144, v148 op_sel_hi:[0,0,0] cbsz:2 blgp:2
	v_mov_b32_e32 v82, v206
	v_mov_b32_e32 v83, v207
	v_mov_b32_e32 v88, v210
	v_mfma_scale_f32_16x16x128_f8f6f4 v[58:61], v[120:125], v[66:71], v[58:61], v174, v148 op_sel_hi:[0,0,0] cbsz:2 blgp:2
	v_mov_b32_e32 v89, v211
	v_mfma_scale_f32_16x16x128_f8f6f4 v[46:49], v[114:119], v[72:77], v[46:49], v144, v198 op_sel_hi:[0,0,0] cbsz:2 blgp:2
	v_mfma_scale_f32_16x16x128_f8f6f4 v[42:45], v[120:125], v[72:77], v[42:45], v174, v198 op_sel_hi:[0,0,0] cbsz:2 blgp:2
	v_mfma_scale_f32_16x16x128_f8f6f4 v[214:217], v[114:119], v[78:83], v[30:33], v144, v208 op_sel_hi:[0,0,0] cbsz:2 blgp:2
	v_mfma_scale_f32_16x16x128_f8f6f4 v[218:221], v[120:125], v[78:83], v[26:29], v174, v208 op_sel_hi:[0,0,0] cbsz:2 blgp:2
	v_mfma_scale_f32_16x16x128_f8f6f4 v[230:233], v[114:119], v[84:89], v[14:17], v144, v212 op_sel_hi:[0,0,0] cbsz:2 blgp:2
	v_mfma_scale_f32_16x16x128_f8f6f4 v[172:175], v[120:125], v[84:89], v[10:13], v174, v212 op_sel_hi:[0,0,0] cbsz:2 blgp:2
	v_mfma_scale_f32_16x16x128_f8f6f4 v[54:57], v[126:131], v[66:71], v[54:57], v200, v148 op_sel_hi:[0,0,0] cbsz:2 blgp:2
	v_mfma_scale_f32_16x16x128_f8f6f4 v[50:53], v[132:137], v[66:71], v[50:53], v204, v148 op_sel_hi:[0,0,0] cbsz:2 blgp:2
	v_mfma_scale_f32_16x16x128_f8f6f4 v[38:41], v[126:131], v[72:77], v[38:41], v200, v198 op_sel_hi:[0,0,0] cbsz:2 blgp:2
	v_mfma_scale_f32_16x16x128_f8f6f4 v[196:199], v[132:137], v[72:77], v[34:37], v204, v198 op_sel_hi:[0,0,0] cbsz:2 blgp:2
	v_mfma_scale_f32_16x16x128_f8f6f4 v[234:237], v[126:131], v[78:83], v[22:25], v200, v208 op_sel_hi:[0,0,0] cbsz:2 blgp:2
	v_mfma_scale_f32_16x16x128_f8f6f4 v[206:209], v[132:137], v[78:83], v[18:21], v204, v208 op_sel_hi:[0,0,0] cbsz:2 blgp:2
	v_mfma_scale_f32_16x16x128_f8f6f4 v[200:203], v[126:131], v[84:89], v[6:9], v200, v212 op_sel_hi:[0,0,0] cbsz:2 blgp:2
	v_mfma_scale_f32_16x16x128_f8f6f4 v[210:213], v[132:137], v[84:89], v[2:5], v204, v212 op_sel_hi:[0,0,0] cbsz:2 blgp:2
	s_barrier
	s_setprio 1
	s_add_i32 s52, 0, 0x18000
	v_add_u32_e32 v6, s52, v1
	s_add_i32 s53, 0, 0x1c000
	ds_read_b128 v[2:5], v6
	ds_read_b128 v[142:145], v6 offset:1024
	ds_read_b128 v[8:11], v6 offset:2048
	ds_read_b128 v[238:241], v6 offset:3072
	v_add_u32_e32 v6, s53, v1
	ds_read_b128 v[114:117], v6
	ds_read_b128 v[242:245], v6 offset:1024
	ds_read_b128 v[120:123], v6 offset:2048
	ds_read_b128 v[246:249], v6 offset:3072
	s_mov_b32 m0, s33
	v_lshl_add_u64 v[6:7], v[252:253], 0, s[14:15]
	ds_read_b128 v[14:17], v178 offset:32768
	ds_read_b128 v[66:69], v178 offset:33792
	ds_read_b128 v[20:23], v178 offset:34816
	ds_read_b128 v[70:73], v178 offset:35840
	ds_read_b128 v[26:29], v178 offset:36864
	ds_read_b128 v[80:83], v178 offset:37888
	ds_read_b128 v[32:35], v178 offset:38912
	ds_read_b128 v[124:127], v178 offset:39936
	global_load_lds_dwordx4 v[6:7], off
	v_lshl_add_u64 v[6:7], v[252:253], 0, s[16:17]
	s_mov_b32 m0, s40
	s_nop 0
	global_load_lds_dwordx4 v[6:7], off
	s_waitcnt vmcnt(8)
	s_waitcnt lgkmcnt(0)
	s_barrier
	s_setprio 0
	s_waitcnt lgkmcnt(0)
	v_mov_b32_e32 v6, v142
	v_mov_b32_e32 v7, v143
	v_mov_b32_e32 v12, v238
	v_mov_b32_e32 v13, v239
	v_mov_b32_e32 v18, v66
	v_mov_b32_e32 v19, v67
	v_mov_b32_e32 v24, v70
	v_mov_b32_e32 v25, v71
	v_mov_b32_e32 v30, v80
	v_mov_b32_e32 v31, v81
	v_mov_b32_e32 v36, v124
	v_mov_b32_e32 v37, v125
	v_mfma_scale_f32_16x16x128_f8f6f4 v[158:161], v[2:7], v[14:19], v[158:161], v144, v68 op_sel_hi:[0,0,0] cbsz:2 blgp:2
	v_mfma_scale_f32_16x16x128_f8f6f4 v[154:157], v[8:13], v[14:19], v[154:157], v240, v68 op_sel_hi:[0,0,0] cbsz:2 blgp:2
	v_mfma_scale_f32_16x16x128_f8f6f4 v[110:113], v[2:7], v[20:25], v[110:113], v144, v72 op_sel_hi:[0,0,0] cbsz:2 blgp:2
	v_mfma_scale_f32_16x16x128_f8f6f4 v[106:109], v[8:13], v[20:25], v[106:109], v240, v72 op_sel_hi:[0,0,0] cbsz:2 blgp:2
	v_mfma_scale_f32_16x16x128_f8f6f4 v[94:97], v[2:7], v[26:31], v[94:97], v144, v82 op_sel_hi:[0,0,0] cbsz:2 blgp:2
	v_mfma_scale_f32_16x16x128_f8f6f4 v[90:93], v[8:13], v[26:31], v[90:93], v240, v82 op_sel_hi:[0,0,0] cbsz:2 blgp:2
	v_mfma_scale_f32_16x16x128_f8f6f4 v[78:81], v[2:7], v[32:37], v[222:225], v144, v126 op_sel_hi:[0,0,0] cbsz:2 blgp:2
	v_mfma_scale_f32_16x16x128_f8f6f4 v[74:77], v[8:13], v[32:37], v[226:229], v240, v126 op_sel_hi:[0,0,0] cbsz:2 blgp:2
	v_mov_b32_e32 v118, v242
	v_mov_b32_e32 v119, v243
	v_mov_b32_e32 v124, v246
	v_mov_b32_e32 v125, v247
	v_mfma_scale_f32_16x16x128_f8f6f4 v[150:153], v[114:119], v[14:19], v[150:153], v244, v68 op_sel_hi:[0,0,0] cbsz:2 blgp:2
	s_nop 0
	v_mfma_scale_f32_16x16x128_f8f6f4 v[146:149], v[120:125], v[14:19], v[138:141], v248, v68 op_sel_hi:[0,0,0] cbsz:2 blgp:2
	v_mfma_scale_f32_16x16x128_f8f6f4 v[102:105], v[114:119], v[20:25], v[102:105], v244, v72 op_sel_hi:[0,0,0] cbsz:2 blgp:2
	v_mfma_scale_f32_16x16x128_f8f6f4 v[98:101], v[120:125], v[20:25], v[98:101], v248, v72 op_sel_hi:[0,0,0] cbsz:2 blgp:2
	v_mfma_scale_f32_16x16x128_f8f6f4 v[86:89], v[114:119], v[26:31], v[180:183], v244, v82 op_sel_hi:[0,0,0] cbsz:2 blgp:2
	v_mfma_scale_f32_16x16x128_f8f6f4 v[82:85], v[120:125], v[26:31], v[184:187], v248, v82 op_sel_hi:[0,0,0] cbsz:2 blgp:2
	v_mfma_scale_f32_16x16x128_f8f6f4 v[70:73], v[114:119], v[32:37], v[188:191], v244, v126 op_sel_hi:[0,0,0] cbsz:2 blgp:2
	v_mfma_scale_f32_16x16x128_f8f6f4 v[66:69], v[120:125], v[32:37], v[192:195], v248, v126 op_sel_hi:[0,0,0] cbsz:2 blgp:2
	s_barrier
	s_setprio 1
	s_add_i32 s52, s52, s25
	v_lshl_add_u64 v[14:15], v[250:251], 0, s[26:27]
	s_mov_b32 m0, s52
	ds_read_b128 v[18:21], v178 offset:49152
	ds_read_b128 v[22:25], v178 offset:50176
	ds_read_b128 v[126:129], v178 offset:51200
	ds_read_b128 v[32:35], v178 offset:52224
	ds_read_b128 v[132:135], v178 offset:53248
	ds_read_b128 v[180:183], v178 offset:54272
	ds_read_b128 v[138:141], v178 offset:55296
	ds_read_b128 v[184:187], v178 offset:56320
	global_load_lds_dwordx4 v[14:15], off
	v_lshl_add_u64 v[14:15], v[250:251], 0, s[30:31]
	s_add_i32 m0, s52, 0x2000
	s_add_i32 s52, s53, s25
	global_load_lds_dwordx4 v[14:15], off
	v_lshl_add_u64 v[14:15], v[250:251], 0, s[34:35]
	s_mov_b32 m0, s52
	s_nop 0
	global_load_lds_dwordx4 v[14:15], off
	v_lshl_add_u64 v[14:15], v[250:251], 0, s[36:37]
	s_add_i32 m0, s52, 0x2000
	s_nop 0
	global_load_lds_dwordx4 v[14:15], off
	v_lshl_add_u64 v[14:15], v[252:253], 0, s[26:27]
	s_mov_b32 m0, s43
	s_nop 0
	global_load_lds_dwordx4 v[14:15], off
	v_lshl_add_u64 v[14:15], v[252:253], 0, s[30:31]
	s_mov_b32 m0, s45
	s_nop 0
	global_load_lds_dwordx4 v[14:15], off
	s_waitcnt vmcnt(8)
	s_waitcnt lgkmcnt(0)
	s_barrier
	s_setprio 0
	s_waitcnt lgkmcnt(0)
	v_mov_b32_e32 v130, v32
	v_mov_b32_e32 v131, v33
	v_mov_b32_e32 v136, v180
	v_mov_b32_e32 v137, v181
	v_mov_b32_e32 v142, v184
	v_mov_b32_e32 v143, v185
	v_mfma_scale_f32_16x16x128_f8f6f4 v[62:65], v[2:7], v[18:23], v[62:65], v144, v24 op_sel_hi:[0,0,0] cbsz:2 blgp:2
	v_mfma_scale_f32_16x16x128_f8f6f4 v[58:61], v[8:13], v[18:23], v[58:61], v240, v24 op_sel_hi:[0,0,0] cbsz:2 blgp:2
	v_mfma_scale_f32_16x16x128_f8f6f4 v[46:49], v[2:7], v[126:131], v[46:49], v144, v34 op_sel_hi:[0,0,0] cbsz:2 blgp:2
	v_mfma_scale_f32_16x16x128_f8f6f4 v[42:45], v[8:13], v[126:131], v[42:45], v240, v34 op_sel_hi:[0,0,0] cbsz:2 blgp:2
	v_mfma_scale_f32_16x16x128_f8f6f4 v[30:33], v[2:7], v[132:137], v[214:217], v144, v182 op_sel_hi:[0,0,0] cbsz:2 blgp:2
	v_mfma_scale_f32_16x16x128_f8f6f4 v[26:29], v[8:13], v[132:137], v[218:221], v240, v182 op_sel_hi:[0,0,0] cbsz:2 blgp:2
	v_mfma_scale_f32_16x16x128_f8f6f4 v[14:17], v[2:7], v[138:143], v[230:233], v144, v186 op_sel_hi:[0,0,0] cbsz:2 blgp:2
	v_mfma_scale_f32_16x16x128_f8f6f4 v[10:13], v[8:13], v[138:143], v[172:175], v240, v186 op_sel_hi:[0,0,0] cbsz:2 blgp:2
	v_mfma_scale_f32_16x16x128_f8f6f4 v[54:57], v[114:119], v[18:23], v[54:57], v244, v24 op_sel_hi:[0,0,0] cbsz:2 blgp:2
	v_mfma_scale_f32_16x16x128_f8f6f4 v[50:53], v[120:125], v[18:23], v[50:53], v248, v24 op_sel_hi:[0,0,0] cbsz:2 blgp:2
	v_mfma_scale_f32_16x16x128_f8f6f4 v[38:41], v[114:119], v[126:131], v[38:41], v244, v34 op_sel_hi:[0,0,0] cbsz:2 blgp:2
	v_mfma_scale_f32_16x16x128_f8f6f4 v[34:37], v[120:125], v[126:131], v[196:199], v248, v34 op_sel_hi:[0,0,0] cbsz:2 blgp:2
	v_mfma_scale_f32_16x16x128_f8f6f4 v[22:25], v[114:119], v[132:137], v[234:237], v244, v182 op_sel_hi:[0,0,0] cbsz:2 blgp:2
	v_mfma_scale_f32_16x16x128_f8f6f4 v[18:21], v[120:125], v[132:137], v[206:209], v248, v182 op_sel_hi:[0,0,0] cbsz:2 blgp:2
	v_mfma_scale_f32_16x16x128_f8f6f4 v[6:9], v[114:119], v[138:143], v[200:203], v244, v186 op_sel_hi:[0,0,0] cbsz:2 blgp:2
	v_mfma_scale_f32_16x16x128_f8f6f4 v[2:5], v[120:125], v[138:143], v[210:213], v248, v186 op_sel_hi:[0,0,0] cbsz:2 blgp:2
	s_barrier
	s_setprio 1
	s_add_i32 s63, s63, 2
	s_add_u32 s48, s48, 0x100
	s_addc_u32 s49, s49, 0
	s_add_u32 s4, s4, 0x100
	s_addc_u32 s5, s5, 0
	s_cmp_gt_u32 s63, 41
	s_cbranch_scc0 .LBB0_1074
	s_setprio 0
	s_and_b64 vcc, exec, s[38:39]
	s_cbranch_vccz .LBB0_1077
	s_barrier

.LBB0_2187:
	ds_read_b128 v[142:145], v138
	ds_read_b128 v[188:191], v138 offset:1024
	ds_read_b128 v[148:151], v138 offset:2048
	ds_read_b128 v[192:195], v138 offset:3072
	ds_read_b128 v[154:157], v139
	ds_read_b128 v[196:199], v139 offset:1024
	ds_read_b128 v[160:163], v139 offset:2048
	ds_read_b128 v[200:203], v139 offset:3072
	v_lshl_add_u64 v[146:147], s[48:49], 0, v[136:137]
	s_add_i32 m0, s33, 0xc000
	ds_read_b128 v[166:169], v140
	ds_read_b128 v[204:207], v140 offset:1024
	ds_read_b128 v[172:175], v140 offset:2048
	ds_read_b128 v[208:211], v140 offset:3072
	ds_read_b128 v[178:181], v140 offset:4096
	ds_read_b128 v[212:215], v140 offset:5120
	ds_read_b128 v[184:187], v140 offset:6144
	ds_read_b128 v[216:219], v140 offset:7168
	global_load_lds_dwordx4 v[146:147], off
	s_add_i32 m0, s33, 0xe000
	v_lshl_add_u64 v[146:147], v[146:147], 0, s[6:7]
	global_load_lds_dwordx4 v[146:147], off
	s_waitcnt vmcnt(8)
	s_waitcnt lgkmcnt(0)
	s_barrier
	s_setprio 0
	s_waitcnt lgkmcnt(0)
	v_mov_b32_e32 v146, v188
	v_mov_b32_e32 v147, v189
	v_mov_b32_e32 v152, v192
	v_mov_b32_e32 v153, v193
	v_mov_b32_e32 v170, v204
	v_mov_b32_e32 v171, v205
	v_mov_b32_e32 v176, v208
	v_mov_b32_e32 v177, v209
	v_mov_b32_e32 v182, v212
	v_mov_b32_e32 v183, v213
	v_mov_b32_e32 v188, v216
	v_mov_b32_e32 v189, v217
	v_mfma_scale_f32_16x16x128_f8f6f4 v[128:131], v[142:147], v[166:171], v[128:131], v190, v206 op_sel_hi:[0,0,0] cbsz:2 blgp:2
	v_mfma_scale_f32_16x16x128_f8f6f4 v[124:127], v[148:153], v[166:171], v[124:127], v194, v206 op_sel_hi:[0,0,0] cbsz:2 blgp:2
	v_mfma_scale_f32_16x16x128_f8f6f4 v[120:123], v[142:147], v[172:177], v[120:123], v190, v210 op_sel_hi:[0,0,0] cbsz:2 blgp:2
	v_mfma_scale_f32_16x16x128_f8f6f4 v[116:119], v[148:153], v[172:177], v[116:119], v194, v210 op_sel_hi:[0,0,0] cbsz:2 blgp:2
	s_add_u32 s50, s48, 0xfffc0080
	s_addc_u32 s51, s49, -1
	s_cmp_eq_u32 s76, 12
	s_cselect_b32 s51, s35, s51
	s_cselect_b32 s50, s47, s50
	s_cselect_b32 s53, s37, s67
	s_cselect_b32 s52, s65, s66
	s_add_i32 s100, s57, s29
	s_add_i32 s101, s58, s29
	v_lshl_add_u64 v[232:233], s[52:53], 0, v[132:133]
	v_lshl_add_u64 v[234:235], s[50:51], 0, v[134:135]
	v_lshl_add_u64 v[240:241], v[232:233], 0, s[6:7]
	v_lshl_add_u64 v[242:243], v[232:233], 0, s[8:9]
	v_lshl_add_u64 v[244:245], v[232:233], 0, s[10:11]
	v_lshl_add_u64 v[246:247], v[234:235], 0, s[6:7]
	v_mfma_scale_f32_16x16x128_f8f6f4 v[112:115], v[142:147], v[178:183], v[112:115], v190, v214 op_sel_hi:[0,0,0] cbsz:2 blgp:2
	v_mfma_scale_f32_16x16x128_f8f6f4 v[108:111], v[148:153], v[178:183], v[108:111], v194, v214 op_sel_hi:[0,0,0] cbsz:2 blgp:2
	v_mfma_scale_f32_16x16x128_f8f6f4 v[104:107], v[142:147], v[184:189], v[104:107], v190, v218 op_sel_hi:[0,0,0] cbsz:2 blgp:2
	v_mfma_scale_f32_16x16x128_f8f6f4 v[100:103], v[148:153], v[184:189], v[100:103], v194, v218 op_sel_hi:[0,0,0] cbsz:2 blgp:2
	v_mov_b32_e32 v164, v200
	v_mov_b32_e32 v165, v201
	v_mov_b32_e32 v158, v196
	v_mov_b32_e32 v159, v197
	v_mfma_scale_f32_16x16x128_f8f6f4 v[30:33], v[160:165], v[184:189], v[30:33], v202, v218 op_sel_hi:[0,0,0] cbsz:2 blgp:2
	s_nop 0
	v_mfma_scale_f32_16x16x128_f8f6f4 v[220:223], v[154:159], v[166:171], v[2:5], v198, v206 op_sel_hi:[0,0,0] cbsz:2 blgp:2
	v_mfma_scale_f32_16x16x128_f8f6f4 v[166:169], v[160:165], v[166:171], v[6:9], v202, v206 op_sel_hi:[0,0,0] cbsz:2 blgp:2
	v_mfma_scale_f32_16x16x128_f8f6f4 v[204:207], v[154:159], v[172:177], v[10:13], v198, v210 op_sel_hi:[0,0,0] cbsz:2 blgp:2
	v_mfma_scale_f32_16x16x128_f8f6f4 v[170:173], v[160:165], v[172:177], v[14:17], v202, v210 op_sel_hi:[0,0,0] cbsz:2 blgp:2
	v_mfma_scale_f32_16x16x128_f8f6f4 v[174:177], v[154:159], v[178:183], v[18:21], v198, v214 op_sel_hi:[0,0,0] cbsz:2 blgp:2
	v_mfma_scale_f32_16x16x128_f8f6f4 v[178:181], v[160:165], v[178:183], v[22:25], v202, v214 op_sel_hi:[0,0,0] cbsz:2 blgp:2
	v_mfma_scale_f32_16x16x128_f8f6f4 v[208:211], v[154:159], v[184:189], v[26:29], v198, v218 op_sel_hi:[0,0,0] cbsz:2 blgp:2
	s_barrier
	s_setprio 1
	s_mov_b32 m0, s100
	ds_read_b128 v[2:5], v140 offset:16384
	ds_read_b128 v[24:27], v140 offset:17408
	ds_read_b128 v[8:11], v140 offset:18432
	global_load_lds_dwordx4 v[232:233], off
	s_add_i32 m0, s100, 0x2000
	ds_read_b128 v[182:185], v140 offset:19456
	global_load_lds_dwordx4 v[240:241], off
	s_mov_b32 m0, s101
	ds_read_b128 v[14:17], v140 offset:20480
	global_load_lds_dwordx4 v[242:243], off
	s_add_i32 m0, s101, 0x2000
	ds_read_b128 v[186:189], v140 offset:21504
	global_load_lds_dwordx4 v[244:245], off
	s_mov_b32 m0, s33
	ds_read_b128 v[20:23], v140 offset:22528
	global_load_lds_dwordx4 v[234:235], off
	s_mov_b32 m0, s40
	ds_read_b128 v[212:215], v140 offset:23552
	global_load_lds_dwordx4 v[246:247], off
	s_waitcnt vmcnt(8)
	s_waitcnt lgkmcnt(0)
	s_barrier
	s_setprio 0
	s_waitcnt lgkmcnt(0)
	v_mov_b32_e32 v6, v24
	v_mov_b32_e32 v7, v25
	v_mov_b32_e32 v12, v182
	v_mov_b32_e32 v13, v183
	v_mov_b32_e32 v18, v186
	v_mov_b32_e32 v19, v187
	v_mfma_scale_f32_16x16x128_f8f6f4 v[96:99], v[142:147], v[2:7], v[96:99], v190, v26 op_sel_hi:[0,0,0] cbsz:2 blgp:2
	v_mov_b32_e32 v24, v212
	v_mov_b32_e32 v25, v213
	v_mfma_scale_f32_16x16x128_f8f6f4 v[92:95], v[148:153], v[2:7], v[92:95], v194, v26 op_sel_hi:[0,0,0] cbsz:2 blgp:2
	v_mfma_scale_f32_16x16x128_f8f6f4 v[80:83], v[142:147], v[8:13], v[80:83], v190, v184 op_sel_hi:[0,0,0] cbsz:2 blgp:2
	v_mfma_scale_f32_16x16x128_f8f6f4 v[76:79], v[148:153], v[8:13], v[76:79], v194, v184 op_sel_hi:[0,0,0] cbsz:2 blgp:2
	s_add_i32 s50, 0, 0x18000
	s_add_i32 s51, 0, 0x1c000
	v_add_u32_e32 v252, 0x18000, v1
	v_add_u32_e32 v253, 0x1c000, v1
	v_lshl_add_u64 v[248:249], v[234:235], 0, s[8:9]
	v_lshl_add_u64 v[250:251], v[234:235], 0, s[10:11]
	v_mfma_scale_f32_16x16x128_f8f6f4 v[68:71], v[142:147], v[14:19], v[68:71], v190, v188 op_sel_hi:[0,0,0] cbsz:2 blgp:2
	v_mfma_scale_f32_16x16x128_f8f6f4 v[56:59], v[148:153], v[14:19], v[56:59], v194, v188 op_sel_hi:[0,0,0] cbsz:2 blgp:2
	v_mfma_scale_f32_16x16x128_f8f6f4 v[190:193], v[142:147], v[20:25], v[52:55], v190, v214 op_sel_hi:[0,0,0] cbsz:2 blgp:2
	v_mfma_scale_f32_16x16x128_f8f6f4 v[194:197], v[148:153], v[20:25], v[44:47], v194, v214 op_sel_hi:[0,0,0] cbsz:2 blgp:2
	v_mfma_scale_f32_16x16x128_f8f6f4 v[88:91], v[154:159], v[2:7], v[88:91], v198, v26 op_sel_hi:[0,0,0] cbsz:2 blgp:2
	v_mfma_scale_f32_16x16x128_f8f6f4 v[84:87], v[160:165], v[2:7], v[84:87], v202, v26 op_sel_hi:[0,0,0] cbsz:2 blgp:2
	v_mfma_scale_f32_16x16x128_f8f6f4 v[72:75], v[154:159], v[8:13], v[72:75], v198, v184 op_sel_hi:[0,0,0] cbsz:2 blgp:2
	v_mfma_scale_f32_16x16x128_f8f6f4 v[182:185], v[160:165], v[8:13], v[64:67], v202, v184 op_sel_hi:[0,0,0] cbsz:2 blgp:2
	v_mfma_scale_f32_16x16x128_f8f6f4 v[216:219], v[154:159], v[14:19], v[60:63], v198, v188 op_sel_hi:[0,0,0] cbsz:2 blgp:2
	v_mfma_scale_f32_16x16x128_f8f6f4 v[186:189], v[160:165], v[14:19], v[48:51], v202, v188 op_sel_hi:[0,0,0] cbsz:2 blgp:2
	v_mfma_scale_f32_16x16x128_f8f6f4 v[198:201], v[154:159], v[20:25], v[40:43], v198, v214 op_sel_hi:[0,0,0] cbsz:2 blgp:2
	v_mfma_scale_f32_16x16x128_f8f6f4 v[212:215], v[160:165], v[20:25], v[36:39], v202, v214 op_sel_hi:[0,0,0] cbsz:2 blgp:2
	s_barrier
	s_setprio 1
	s_mov_b32 m0, s41
	ds_read_b128 v[36:39], v252
	ds_read_b128 v[52:55], v252 offset:1024
	ds_read_b128 v[42:45], v252 offset:2048
	ds_read_b128 v[64:67], v252 offset:3072
	ds_read_b128 v[142:145], v253
	ds_read_b128 v[224:227], v253 offset:1024
	ds_read_b128 v[148:151], v253 offset:2048
	ds_read_b128 v[228:231], v253 offset:3072
	ds_read_b128 v[6:9], v140 offset:32768
	ds_read_b128 v[10:13], v140 offset:33792
	ds_read_b128 v[14:17], v140 offset:34816
	ds_read_b128 v[18:21], v140 offset:35840
	ds_read_b128 v[22:25], v140 offset:36864
	ds_read_b128 v[26:29], v140 offset:37888
	global_load_lds_dwordx4 v[248:249], off
	s_mov_b32 m0, s42
	ds_read_b128 v[48:51], v140 offset:38912
	ds_read_b128 v[60:63], v140 offset:39936
	global_load_lds_dwordx4 v[250:251], off
	s_waitcnt vmcnt(8)
	s_waitcnt lgkmcnt(0)
	s_barrier
	s_setprio 0
	s_waitcnt lgkmcnt(0)
	v_mov_b32_e32 v40, v52
	v_mov_b32_e32 v41, v53
	v_mov_b32_e32 v46, v64
	v_mov_b32_e32 v47, v65
	v_mov_b32_e32 v52, v60
	v_mov_b32_e32 v53, v61
	v_mfma_scale_f32_16x16x128_f8f6f4 v[128:131], v[36:41], v[6:11], v[128:131], v54, v12 op_sel_hi:[0,0,0] cbsz:2 blgp:2
	v_mfma_scale_f32_16x16x128_f8f6f4 v[124:127], v[42:47], v[6:11], v[124:127], v66, v12 op_sel_hi:[0,0,0] cbsz:2 blgp:2
	v_mfma_scale_f32_16x16x128_f8f6f4 v[120:123], v[36:41], v[14:19], v[120:123], v54, v20 op_sel_hi:[0,0,0] cbsz:2 blgp:2
	v_mfma_scale_f32_16x16x128_f8f6f4 v[116:119], v[42:47], v[14:19], v[116:119], v66, v20 op_sel_hi:[0,0,0] cbsz:2 blgp:2
	s_add_i32 s100, s50, s29
	s_add_i32 s101, s51, s29
	s_add_i32 s50, s51, s29
	v_lshl_add_u64 v[240:241], v[232:233], 0, s[20:21]
	v_lshl_add_u64 v[242:243], v[232:233], 0, s[22:23]
	v_lshl_add_u64 v[244:245], v[232:233], 0, s[24:25]
	v_lshl_add_u64 v[246:247], v[232:233], 0, s[26:27]
	v_lshl_add_u64 v[248:249], v[234:235], 0, s[20:21]
	v_lshl_add_u64 v[250:251], v[234:235], 0, s[22:23]
	v_mfma_scale_f32_16x16x128_f8f6f4 v[112:115], v[36:41], v[22:27], v[112:115], v54, v28 op_sel_hi:[0,0,0] cbsz:2 blgp:2
	v_mfma_scale_f32_16x16x128_f8f6f4 v[108:111], v[42:47], v[22:27], v[108:111], v66, v28 op_sel_hi:[0,0,0] cbsz:2 blgp:2
	v_mfma_scale_f32_16x16x128_f8f6f4 v[104:107], v[36:41], v[48:53], v[104:107], v54, v62 op_sel_hi:[0,0,0] cbsz:2 blgp:2
	v_mfma_scale_f32_16x16x128_f8f6f4 v[100:103], v[42:47], v[48:53], v[100:103], v66, v62 op_sel_hi:[0,0,0] cbsz:2 blgp:2
	v_mov_b32_e32 v146, v224
	v_mov_b32_e32 v147, v225
	v_mov_b32_e32 v152, v228
	v_mov_b32_e32 v153, v229
	v_mfma_scale_f32_16x16x128_f8f6f4 v[2:5], v[142:147], v[6:11], v[220:223], v226, v12 op_sel_hi:[0,0,0] cbsz:2 blgp:2
	s_nop 0
	v_mfma_scale_f32_16x16x128_f8f6f4 v[6:9], v[148:153], v[6:11], v[166:169], v230, v12 op_sel_hi:[0,0,0] cbsz:2 blgp:2
	v_mfma_scale_f32_16x16x128_f8f6f4 v[10:13], v[142:147], v[14:19], v[204:207], v226, v20 op_sel_hi:[0,0,0] cbsz:2 blgp:2
	v_mfma_scale_f32_16x16x128_f8f6f4 v[14:17], v[148:153], v[14:19], v[170:173], v230, v20 op_sel_hi:[0,0,0] cbsz:2 blgp:2
	v_mfma_scale_f32_16x16x128_f8f6f4 v[18:21], v[142:147], v[22:27], v[174:177], v226, v28 op_sel_hi:[0,0,0] cbsz:2 blgp:2
	v_mfma_scale_f32_16x16x128_f8f6f4 v[22:25], v[148:153], v[22:27], v[178:181], v230, v28 op_sel_hi:[0,0,0] cbsz:2 blgp:2
	v_mfma_scale_f32_16x16x128_f8f6f4 v[26:29], v[142:147], v[48:53], v[208:211], v226, v62 op_sel_hi:[0,0,0] cbsz:2 blgp:2
	v_mfma_scale_f32_16x16x128_f8f6f4 v[30:33], v[148:153], v[48:53], v[30:33], v230, v62 op_sel_hi:[0,0,0] cbsz:2 blgp:2
	s_barrier
	s_setprio 1
	s_mov_b32 m0, s100
	ds_read_b128 v[60:63], v140 offset:49152
	ds_read_b128 v[48:51], v140 offset:50176
	ds_read_b128 v[154:157], v140 offset:51200
	global_load_lds_dwordx4 v[240:241], off
	s_add_i32 m0, s100, 0x2000
	ds_read_b128 v[170:173], v140 offset:52224
	global_load_lds_dwordx4 v[242:243], off
	s_mov_b32 m0, s101
	ds_read_b128 v[160:163], v140 offset:53248
	global_load_lds_dwordx4 v[244:245], off
	s_add_i32 m0, s101, 0x2000
	ds_read_b128 v[174:177], v140 offset:54272
	global_load_lds_dwordx4 v[246:247], off
	s_mov_b32 m0, s43
	ds_read_b128 v[166:169], v140 offset:55296
	global_load_lds_dwordx4 v[248:249], off
	s_mov_b32 m0, s54
	ds_read_b128 v[178:181], v140 offset:56320
	global_load_lds_dwordx4 v[250:251], off
	s_waitcnt vmcnt(8)
	s_waitcnt lgkmcnt(0)
	s_barrier
	s_setprio 0
	s_waitcnt lgkmcnt(0)
	v_mov_b32_e32 v64, v48
	v_mov_b32_e32 v65, v49
	v_mov_b32_e32 v158, v170
	v_mov_b32_e32 v159, v171
	v_mov_b32_e32 v164, v174
	v_mov_b32_e32 v165, v175
	v_mov_b32_e32 v170, v178
	v_mov_b32_e32 v171, v179
	v_mfma_scale_f32_16x16x128_f8f6f4 v[96:99], v[36:41], v[60:65], v[96:99], v54, v50 op_sel_hi:[0,0,0] cbsz:2 blgp:2
	v_mfma_scale_f32_16x16x128_f8f6f4 v[92:95], v[42:47], v[60:65], v[92:95], v66, v50 op_sel_hi:[0,0,0] cbsz:2 blgp:2
	v_mfma_scale_f32_16x16x128_f8f6f4 v[80:83], v[36:41], v[154:159], v[80:83], v54, v172 op_sel_hi:[0,0,0] cbsz:2 blgp:2
	v_mfma_scale_f32_16x16x128_f8f6f4 v[76:79], v[42:47], v[154:159], v[76:79], v66, v172 op_sel_hi:[0,0,0] cbsz:2 blgp:2
	s_add_i32 s76, s76, 2
	s_add_u32 s48, s48, 0x100
	s_addc_u32 s49, s49, 0
	s_add_u32 s66, s66, 0x100
	s_addc_u32 s67, s67, 0
	v_mfma_scale_f32_16x16x128_f8f6f4 v[68:71], v[36:41], v[160:165], v[68:71], v54, v176 op_sel_hi:[0,0,0] cbsz:2 blgp:2
	v_mfma_scale_f32_16x16x128_f8f6f4 v[56:59], v[42:47], v[160:165], v[56:59], v66, v176 op_sel_hi:[0,0,0] cbsz:2 blgp:2
	v_mfma_scale_f32_16x16x128_f8f6f4 v[52:55], v[36:41], v[166:171], v[190:193], v54, v180 op_sel_hi:[0,0,0] cbsz:2 blgp:2
	v_mfma_scale_f32_16x16x128_f8f6f4 v[44:47], v[42:47], v[166:171], v[194:197], v66, v180 op_sel_hi:[0,0,0] cbsz:2 blgp:2
	v_mfma_scale_f32_16x16x128_f8f6f4 v[88:91], v[142:147], v[60:65], v[88:91], v226, v50 op_sel_hi:[0,0,0] cbsz:2 blgp:2
	v_mfma_scale_f32_16x16x128_f8f6f4 v[84:87], v[148:153], v[60:65], v[84:87], v230, v50 op_sel_hi:[0,0,0] cbsz:2 blgp:2
	v_mfma_scale_f32_16x16x128_f8f6f4 v[72:75], v[142:147], v[154:159], v[72:75], v226, v172 op_sel_hi:[0,0,0] cbsz:2 blgp:2
	v_mfma_scale_f32_16x16x128_f8f6f4 v[64:67], v[148:153], v[154:159], v[182:185], v230, v172 op_sel_hi:[0,0,0] cbsz:2 blgp:2
	v_mfma_scale_f32_16x16x128_f8f6f4 v[60:63], v[142:147], v[160:165], v[216:219], v226, v176 op_sel_hi:[0,0,0] cbsz:2 blgp:2
	v_mfma_scale_f32_16x16x128_f8f6f4 v[48:51], v[148:153], v[160:165], v[186:189], v230, v176 op_sel_hi:[0,0,0] cbsz:2 blgp:2
	v_mfma_scale_f32_16x16x128_f8f6f4 v[40:43], v[142:147], v[166:171], v[198:201], v226, v180 op_sel_hi:[0,0,0] cbsz:2 blgp:2
	v_mfma_scale_f32_16x16x128_f8f6f4 v[36:39], v[148:153], v[166:171], v[212:215], v230, v180 op_sel_hi:[0,0,0] cbsz:2 blgp:2
	s_barrier
	s_setprio 1
	s_cmp_gt_u32 s76, 13
	s_cbranch_scc0 .LBB0_2187
	s_setprio 0
	s_and_b64 vcc, exec, s[30:31]
	s_cbranch_vccz .LBB0_2190
	s_barrier

.LBB0_2291:
	ds_read_b128 v[144:147], v140
	ds_read_b128 v[190:193], v140 offset:1024
	ds_read_b128 v[150:153], v140 offset:2048
	ds_read_b128 v[194:197], v140 offset:3072
	ds_read_b128 v[156:159], v141
	ds_read_b128 v[198:201], v141 offset:1024
	ds_read_b128 v[162:165], v141 offset:2048
	ds_read_b128 v[202:205], v141 offset:3072
	v_lshl_add_u64 v[138:139], s[44:45], 0, v[136:137]
	s_add_i32 m0, s33, 0xc000
	ds_read_b128 v[168:171], v142
	ds_read_b128 v[206:209], v142 offset:1024
	ds_read_b128 v[174:177], v142 offset:2048
	ds_read_b128 v[210:213], v142 offset:3072
	ds_read_b128 v[180:183], v142 offset:4096
	ds_read_b128 v[214:217], v142 offset:5120
	ds_read_b128 v[186:189], v142 offset:6144
	ds_read_b128 v[218:221], v142 offset:7168
	global_load_lds_dwordx4 v[138:139], off
	s_add_i32 m0, s33, 0xe000
	v_lshl_add_u64 v[138:139], v[138:139], 0, s[8:9]
	global_load_lds_dwordx4 v[138:139], off
	s_waitcnt vmcnt(8)
	s_waitcnt lgkmcnt(0)
	s_barrier
	s_setprio 0
	s_waitcnt lgkmcnt(0)
	v_mov_b32_e32 v148, v190
	v_mov_b32_e32 v149, v191
	v_mov_b32_e32 v154, v194
	v_mov_b32_e32 v155, v195
	v_mov_b32_e32 v172, v206
	v_mov_b32_e32 v173, v207
	v_mov_b32_e32 v178, v210
	v_mov_b32_e32 v179, v211
	v_mov_b32_e32 v184, v214
	v_mov_b32_e32 v185, v215
	v_mfma_scale_f32_16x16x128_f8f6f4 v[126:129], v[144:149], v[168:173], v[126:129], v192, v208 op_sel_hi:[0,0,0] cbsz:2 blgp:2
	v_mov_b32_e32 v190, v218
	v_mov_b32_e32 v191, v219
	v_mfma_scale_f32_16x16x128_f8f6f4 v[122:125], v[150:155], v[168:173], v[122:125], v196, v208 op_sel_hi:[0,0,0] cbsz:2 blgp:2
	v_mfma_scale_f32_16x16x128_f8f6f4 v[110:113], v[144:149], v[174:179], v[110:113], v192, v212 op_sel_hi:[0,0,0] cbsz:2 blgp:2
	v_mfma_scale_f32_16x16x128_f8f6f4 v[106:109], v[150:155], v[174:179], v[106:109], v196, v212 op_sel_hi:[0,0,0] cbsz:2 blgp:2
	s_add_i32 s76, s46, 2
	s_add_u32 s48, s44, 0xfff20080
	s_addc_u32 s47, s45, -1
	s_cmp_eq_u32 s4, s46
	s_cselect_b32 s46, s38, s48
	s_cselect_b32 s47, s39, s47
	s_cselect_b32 s49, s7, s67
	s_cselect_b32 s48, s6, s5
	s_add_i32 s100, s58, s29
	s_add_i32 s101, s59, s29
	v_lshl_add_u64 v[138:139], s[48:49], 0, v[132:133]
	v_lshl_add_u64 v[246:247], s[46:47], 0, v[130:131]
	v_lshl_add_u64 v[248:249], v[138:139], 0, s[8:9]
	v_lshl_add_u64 v[250:251], v[138:139], 0, s[10:11]
	v_lshl_add_u64 v[252:253], v[138:139], 0, s[12:13]
	v_mfma_scale_f32_16x16x128_f8f6f4 v[94:97], v[144:149], v[180:185], v[94:97], v192, v216 op_sel_hi:[0,0,0] cbsz:2 blgp:2
	v_mfma_scale_f32_16x16x128_f8f6f4 v[90:93], v[150:155], v[180:185], v[90:93], v196, v216 op_sel_hi:[0,0,0] cbsz:2 blgp:2
	v_mfma_scale_f32_16x16x128_f8f6f4 v[222:225], v[144:149], v[186:191], v[78:81], v192, v220 op_sel_hi:[0,0,0] cbsz:2 blgp:2
	v_mfma_scale_f32_16x16x128_f8f6f4 v[226:229], v[150:155], v[186:191], v[74:77], v196, v220 op_sel_hi:[0,0,0] cbsz:2 blgp:2
	v_mov_b32_e32 v160, v198
	v_mov_b32_e32 v161, v199
	v_mov_b32_e32 v166, v202
	v_mov_b32_e32 v167, v203
	v_mfma_scale_f32_16x16x128_f8f6f4 v[118:121], v[156:161], v[168:173], v[118:121], v200, v208 op_sel_hi:[0,0,0] cbsz:2 blgp:2
	s_nop 0
	v_mfma_scale_f32_16x16x128_f8f6f4 v[114:117], v[162:167], v[168:173], v[114:117], v204, v208 op_sel_hi:[0,0,0] cbsz:2 blgp:2
	v_mfma_scale_f32_16x16x128_f8f6f4 v[102:105], v[156:161], v[174:179], v[102:105], v200, v212 op_sel_hi:[0,0,0] cbsz:2 blgp:2
	v_mfma_scale_f32_16x16x128_f8f6f4 v[98:101], v[162:167], v[174:179], v[98:101], v204, v212 op_sel_hi:[0,0,0] cbsz:2 blgp:2
	v_mfma_scale_f32_16x16x128_f8f6f4 v[168:171], v[156:161], v[180:185], v[86:89], v200, v216 op_sel_hi:[0,0,0] cbsz:2 blgp:2
	v_mfma_scale_f32_16x16x128_f8f6f4 v[172:175], v[162:167], v[180:185], v[82:85], v204, v216 op_sel_hi:[0,0,0] cbsz:2 blgp:2
	v_mfma_scale_f32_16x16x128_f8f6f4 v[176:179], v[156:161], v[186:191], v[70:73], v200, v220 op_sel_hi:[0,0,0] cbsz:2 blgp:2
	v_mfma_scale_f32_16x16x128_f8f6f4 v[180:183], v[162:167], v[186:191], v[66:69], v204, v220 op_sel_hi:[0,0,0] cbsz:2 blgp:2
	s_barrier
	s_setprio 1
	s_mov_b32 m0, s100
	ds_read_b128 v[66:69], v142 offset:16384
	ds_read_b128 v[184:187], v142 offset:17408
	ds_read_b128 v[72:75], v142 offset:18432
	global_load_lds_dwordx4 v[138:139], off
	s_add_i32 m0, s100, 0x2000
	ds_read_b128 v[188:191], v142 offset:19456
	global_load_lds_dwordx4 v[248:249], off
	s_mov_b32 m0, s101
	ds_read_b128 v[78:81], v142 offset:20480
	global_load_lds_dwordx4 v[250:251], off
	s_add_i32 m0, s101, 0x2000
	ds_read_b128 v[206:209], v142 offset:21504
	global_load_lds_dwordx4 v[252:253], off
	s_mov_b32 m0, s33
	ds_read_b128 v[84:87], v142 offset:22528
	global_load_lds_dwordx4 v[246:247], off
	s_mov_b32 m0, s40
	v_lshl_add_u64 v[70:71], v[246:247], 0, s[8:9]
	ds_read_b128 v[210:213], v142 offset:23552
	global_load_lds_dwordx4 v[70:71], off
	s_waitcnt vmcnt(8)
	s_waitcnt lgkmcnt(0)
	s_barrier
	s_setprio 0
	s_waitcnt lgkmcnt(0)
	v_mov_b32_e32 v70, v184
	v_mov_b32_e32 v71, v185
	v_mov_b32_e32 v76, v188
	v_mov_b32_e32 v77, v189
	v_mfma_scale_f32_16x16x128_f8f6f4 v[62:65], v[144:149], v[66:71], v[62:65], v192, v186 op_sel_hi:[0,0,0] cbsz:2 blgp:2
	v_mov_b32_e32 v82, v206
	v_mov_b32_e32 v83, v207
	v_mov_b32_e32 v88, v210
	v_mfma_scale_f32_16x16x128_f8f6f4 v[58:61], v[150:155], v[66:71], v[58:61], v196, v186 op_sel_hi:[0,0,0] cbsz:2 blgp:2
	v_mov_b32_e32 v89, v211
	v_mfma_scale_f32_16x16x128_f8f6f4 v[46:49], v[144:149], v[72:77], v[46:49], v192, v190 op_sel_hi:[0,0,0] cbsz:2 blgp:2
	v_mfma_scale_f32_16x16x128_f8f6f4 v[42:45], v[150:155], v[72:77], v[42:45], v196, v190 op_sel_hi:[0,0,0] cbsz:2 blgp:2
	s_add_i32 s46, 0, 0x18000
	s_add_i32 s47, 0, 0x1c000
	v_add_u32_e32 v143, 0x18000, v1
	v_add_u32_e32 v134, 0x1c000, v1
	v_lshl_add_u64 v[248:249], v[246:247], 0, s[10:11]
	v_lshl_add_u64 v[250:251], v[246:247], 0, s[12:13]
	v_mfma_scale_f32_16x16x128_f8f6f4 v[214:217], v[144:149], v[78:83], v[30:33], v192, v208 op_sel_hi:[0,0,0] cbsz:2 blgp:2
	v_mfma_scale_f32_16x16x128_f8f6f4 v[218:221], v[150:155], v[78:83], v[26:29], v196, v208 op_sel_hi:[0,0,0] cbsz:2 blgp:2
	v_mfma_scale_f32_16x16x128_f8f6f4 v[192:195], v[144:149], v[84:89], v[14:17], v192, v212 op_sel_hi:[0,0,0] cbsz:2 blgp:2
	v_mfma_scale_f32_16x16x128_f8f6f4 v[196:199], v[150:155], v[84:89], v[10:13], v196, v212 op_sel_hi:[0,0,0] cbsz:2 blgp:2
	v_mfma_scale_f32_16x16x128_f8f6f4 v[54:57], v[156:161], v[66:71], v[54:57], v200, v186 op_sel_hi:[0,0,0] cbsz:2 blgp:2
	v_mfma_scale_f32_16x16x128_f8f6f4 v[50:53], v[162:167], v[66:71], v[50:53], v204, v186 op_sel_hi:[0,0,0] cbsz:2 blgp:2
	v_mfma_scale_f32_16x16x128_f8f6f4 v[38:41], v[156:161], v[72:77], v[38:41], v200, v190 op_sel_hi:[0,0,0] cbsz:2 blgp:2
	v_mfma_scale_f32_16x16x128_f8f6f4 v[184:187], v[162:167], v[72:77], v[34:37], v204, v190 op_sel_hi:[0,0,0] cbsz:2 blgp:2
	v_mfma_scale_f32_16x16x128_f8f6f4 v[188:191], v[156:161], v[78:83], v[22:25], v200, v208 op_sel_hi:[0,0,0] cbsz:2 blgp:2
	v_mfma_scale_f32_16x16x128_f8f6f4 v[206:209], v[162:167], v[78:83], v[18:21], v204, v208 op_sel_hi:[0,0,0] cbsz:2 blgp:2
	v_mfma_scale_f32_16x16x128_f8f6f4 v[200:203], v[156:161], v[84:89], v[6:9], v200, v212 op_sel_hi:[0,0,0] cbsz:2 blgp:2
	v_mfma_scale_f32_16x16x128_f8f6f4 v[210:213], v[162:167], v[84:89], v[2:5], v204, v212 op_sel_hi:[0,0,0] cbsz:2 blgp:2
	s_barrier
	s_setprio 1
	s_mov_b32 m0, s41
	ds_read_b128 v[2:5], v143
	ds_read_b128 v[230:233], v143 offset:1024
	ds_read_b128 v[8:11], v143 offset:2048
	ds_read_b128 v[234:237], v143 offset:3072
	ds_read_b128 v[144:147], v134
	ds_read_b128 v[238:241], v134 offset:1024
	ds_read_b128 v[150:153], v134 offset:2048
	ds_read_b128 v[242:245], v134 offset:3072
	ds_read_b128 v[14:17], v142 offset:32768
	ds_read_b128 v[66:69], v142 offset:33792
	ds_read_b128 v[20:23], v142 offset:34816
	ds_read_b128 v[70:73], v142 offset:35840
	ds_read_b128 v[26:29], v142 offset:36864
	ds_read_b128 v[80:83], v142 offset:37888
	global_load_lds_dwordx4 v[248:249], off
	s_mov_b32 m0, s42
	ds_read_b128 v[32:35], v142 offset:38912
	ds_read_b128 v[154:157], v142 offset:39936
	global_load_lds_dwordx4 v[250:251], off
	s_waitcnt vmcnt(8)
	s_waitcnt lgkmcnt(0)
	s_barrier
	s_setprio 0
	s_waitcnt lgkmcnt(0)
	v_mov_b32_e32 v6, v230
	v_mov_b32_e32 v7, v231
	v_mov_b32_e32 v12, v234
	v_mov_b32_e32 v13, v235
	v_mov_b32_e32 v18, v66
	v_mov_b32_e32 v19, v67
	v_mov_b32_e32 v24, v70
	v_mov_b32_e32 v25, v71
	v_mov_b32_e32 v30, v80
	v_mov_b32_e32 v31, v81
	v_mov_b32_e32 v36, v154
	v_mov_b32_e32 v37, v155
	v_mfma_scale_f32_16x16x128_f8f6f4 v[126:129], v[2:7], v[14:19], v[126:129], v232, v68 op_sel_hi:[0,0,0] cbsz:2 blgp:2
	v_mfma_scale_f32_16x16x128_f8f6f4 v[122:125], v[8:13], v[14:19], v[122:125], v236, v68 op_sel_hi:[0,0,0] cbsz:2 blgp:2
	v_mfma_scale_f32_16x16x128_f8f6f4 v[110:113], v[2:7], v[20:25], v[110:113], v232, v72 op_sel_hi:[0,0,0] cbsz:2 blgp:2
	v_mfma_scale_f32_16x16x128_f8f6f4 v[106:109], v[8:13], v[20:25], v[106:109], v236, v72 op_sel_hi:[0,0,0] cbsz:2 blgp:2
	s_add_i32 s100, s46, s29
	s_add_i32 s101, s47, s29
	s_add_i32 s46, s47, s29
	v_lshl_add_u64 v[248:249], v[138:139], 0, s[24:25]
	v_lshl_add_u64 v[250:251], v[138:139], 0, s[26:27]
	v_lshl_add_u64 v[252:253], v[138:139], 0, s[30:31]
	v_mfma_scale_f32_16x16x128_f8f6f4 v[94:97], v[2:7], v[26:31], v[94:97], v232, v82 op_sel_hi:[0,0,0] cbsz:2 blgp:2
	v_mfma_scale_f32_16x16x128_f8f6f4 v[90:93], v[8:13], v[26:31], v[90:93], v236, v82 op_sel_hi:[0,0,0] cbsz:2 blgp:2
	v_mfma_scale_f32_16x16x128_f8f6f4 v[78:81], v[2:7], v[32:37], v[222:225], v232, v156 op_sel_hi:[0,0,0] cbsz:2 blgp:2
	v_mfma_scale_f32_16x16x128_f8f6f4 v[74:77], v[8:13], v[32:37], v[226:229], v236, v156 op_sel_hi:[0,0,0] cbsz:2 blgp:2
	v_mov_b32_e32 v148, v238
	v_mov_b32_e32 v149, v239
	v_mov_b32_e32 v154, v242
	v_mov_b32_e32 v155, v243
	v_mfma_scale_f32_16x16x128_f8f6f4 v[118:121], v[144:149], v[14:19], v[118:121], v240, v68 op_sel_hi:[0,0,0] cbsz:2 blgp:2
	s_nop 0
	v_mfma_scale_f32_16x16x128_f8f6f4 v[114:117], v[150:155], v[14:19], v[114:117], v244, v68 op_sel_hi:[0,0,0] cbsz:2 blgp:2
	v_mfma_scale_f32_16x16x128_f8f6f4 v[102:105], v[144:149], v[20:25], v[102:105], v240, v72 op_sel_hi:[0,0,0] cbsz:2 blgp:2
	v_mfma_scale_f32_16x16x128_f8f6f4 v[98:101], v[150:155], v[20:25], v[98:101], v244, v72 op_sel_hi:[0,0,0] cbsz:2 blgp:2
	v_mfma_scale_f32_16x16x128_f8f6f4 v[86:89], v[144:149], v[26:31], v[168:171], v240, v82 op_sel_hi:[0,0,0] cbsz:2 blgp:2
	v_mfma_scale_f32_16x16x128_f8f6f4 v[82:85], v[150:155], v[26:31], v[172:175], v244, v82 op_sel_hi:[0,0,0] cbsz:2 blgp:2
	v_mfma_scale_f32_16x16x128_f8f6f4 v[70:73], v[144:149], v[32:37], v[176:179], v240, v156 op_sel_hi:[0,0,0] cbsz:2 blgp:2
	v_mfma_scale_f32_16x16x128_f8f6f4 v[66:69], v[150:155], v[32:37], v[180:183], v244, v156 op_sel_hi:[0,0,0] cbsz:2 blgp:2
	s_barrier
	s_setprio 1
	s_mov_b32 m0, s100
	ds_read_b128 v[18:21], v142 offset:49152
	ds_read_b128 v[22:25], v142 offset:50176
	ds_read_b128 v[156:159], v142 offset:51200
	global_load_lds_dwordx4 v[248:249], off
	s_add_i32 m0, s100, 0x2000
	ds_read_b128 v[32:35], v142 offset:52224
	global_load_lds_dwordx4 v[250:251], off
	s_mov_b32 m0, s101
	ds_read_b128 v[162:165], v142 offset:53248
	global_load_lds_dwordx4 v[252:253], off
	s_add_i32 m0, s101, 0x2000
	v_lshl_add_u64 v[14:15], v[138:139], 0, s[34:35]
	ds_read_b128 v[172:175], v142 offset:54272
	global_load_lds_dwordx4 v[14:15], off
	s_mov_b32 m0, s51
	v_lshl_add_u64 v[14:15], v[246:247], 0, s[24:25]
	ds_read_b128 v[168:171], v142 offset:55296
	global_load_lds_dwordx4 v[14:15], off
	s_mov_b32 m0, s52
	v_lshl_add_u64 v[14:15], v[246:247], 0, s[26:27]
	ds_read_b128 v[176:179], v142 offset:56320
	global_load_lds_dwordx4 v[14:15], off
	s_waitcnt vmcnt(8)
	s_waitcnt lgkmcnt(0)
	s_barrier
	s_setprio 0
	s_waitcnt lgkmcnt(0)
	v_mov_b32_e32 v160, v32
	v_mov_b32_e32 v161, v33
	v_mov_b32_e32 v166, v172
	v_mov_b32_e32 v167, v173
	v_mov_b32_e32 v172, v176
	v_mov_b32_e32 v173, v177
	v_mfma_scale_f32_16x16x128_f8f6f4 v[62:65], v[2:7], v[18:23], v[62:65], v232, v24 op_sel_hi:[0,0,0] cbsz:2 blgp:2
	v_mfma_scale_f32_16x16x128_f8f6f4 v[58:61], v[8:13], v[18:23], v[58:61], v236, v24 op_sel_hi:[0,0,0] cbsz:2 blgp:2
	v_mfma_scale_f32_16x16x128_f8f6f4 v[46:49], v[2:7], v[156:161], v[46:49], v232, v34 op_sel_hi:[0,0,0] cbsz:2 blgp:2
	v_mfma_scale_f32_16x16x128_f8f6f4 v[42:45], v[8:13], v[156:161], v[42:45], v236, v34 op_sel_hi:[0,0,0] cbsz:2 blgp:2
	v_mfma_scale_f32_16x16x128_f8f6f4 v[30:33], v[2:7], v[162:167], v[214:217], v232, v174 op_sel_hi:[0,0,0] cbsz:2 blgp:2
	v_mfma_scale_f32_16x16x128_f8f6f4 v[26:29], v[8:13], v[162:167], v[218:221], v236, v174 op_sel_hi:[0,0,0] cbsz:2 blgp:2
	v_mfma_scale_f32_16x16x128_f8f6f4 v[14:17], v[2:7], v[168:173], v[192:195], v232, v178 op_sel_hi:[0,0,0] cbsz:2 blgp:2
	v_mfma_scale_f32_16x16x128_f8f6f4 v[10:13], v[8:13], v[168:173], v[196:199], v236, v178 op_sel_hi:[0,0,0] cbsz:2 blgp:2
	v_mfma_scale_f32_16x16x128_f8f6f4 v[54:57], v[144:149], v[18:23], v[54:57], v240, v24 op_sel_hi:[0,0,0] cbsz:2 blgp:2
	v_mfma_scale_f32_16x16x128_f8f6f4 v[50:53], v[150:155], v[18:23], v[50:53], v244, v24 op_sel_hi:[0,0,0] cbsz:2 blgp:2
	v_mfma_scale_f32_16x16x128_f8f6f4 v[38:41], v[144:149], v[156:161], v[38:41], v240, v34 op_sel_hi:[0,0,0] cbsz:2 blgp:2
	v_mfma_scale_f32_16x16x128_f8f6f4 v[34:37], v[150:155], v[156:161], v[184:187], v244, v34 op_sel_hi:[0,0,0] cbsz:2 blgp:2
	v_mfma_scale_f32_16x16x128_f8f6f4 v[22:25], v[144:149], v[162:167], v[188:191], v240, v174 op_sel_hi:[0,0,0] cbsz:2 blgp:2
	v_mfma_scale_f32_16x16x128_f8f6f4 v[18:21], v[150:155], v[162:167], v[206:209], v244, v174 op_sel_hi:[0,0,0] cbsz:2 blgp:2
	v_mfma_scale_f32_16x16x128_f8f6f4 v[6:9], v[144:149], v[168:173], v[200:203], v240, v178 op_sel_hi:[0,0,0] cbsz:2 blgp:2
	v_mfma_scale_f32_16x16x128_f8f6f4 v[2:5], v[150:155], v[168:173], v[210:213], v244, v178 op_sel_hi:[0,0,0] cbsz:2 blgp:2
	s_barrier
	s_setprio 1
	s_add_u32 s44, s44, 0x100
	s_addc_u32 s45, s45, 0
	s_add_u32 s5, s5, 0x100
	s_addc_u32 s67, s67, 0
	s_cmp_ge_i32 s76, s66
	s_mov_b32 s46, s76
	s_cbranch_scc0 .LBB0_2291
	s_setprio 0
	v_readlane_b32 s76, v254, 6
	v_readlane_b32 s77, v254, 7
	v_readlane_b32 s78, v254, 8
	v_readlane_b32 s79, v254, 9
	v_readlane_b32 s80, v254, 10
	v_readlane_b32 s81, v254, 11
	v_readlane_b32 s82, v254, 12
	v_readlane_b32 s83, v254, 13
	s_and_b64 vcc, exec, s[36:37]
	s_cbranch_vccz .LBB0_2294
